# RWKV producer done-flag poll: both flag words read behind a single lgkmcnt wait instead of two serialized LDS round trips
# speedup vs baseline: 1.0013x; 1.0013x over previous
; __device__ __forceinline__ void rw_wy(const Args& a, LAS unsigned char* lds, int bh, int tid) {
;     ...
;         for (int c = c_first; c < WY_NCH; c += WY_NP) {
;             while (min(__hip_atomic_load(flags + 8, __ATOMIC_ACQUIRE, __HIP_MEMORY_SCOPE_WORKGROUP), __hip_atomic_load(flags + 9, __ATOMIC_ACQUIRE, __HIP_MEMORY_SCOPE_WORKGROUP)) < c - (WY_NP - 1)) __builtin_amdgcn_s_sleep(2);
.LBB0_1422:
	s_add_i32 s0, 0, 0x19e20
	v_mov_b32_e32 v16, s0
	v_mov_b32_e32 v17, s46
	ds_read_b32 v16, v16
	ds_read_b32 v17, v17
	s_waitcnt lgkmcnt(0)
	s_add_i32 s1, s90, -5
	v_min_i32_e32 v16, v16, v17
	v_cmp_le_i32_e32 vcc, s1, v16
	s_cbranch_vccnz .LBB0_1424
.LBB0_1423:
	v_mov_b32_e32 v16, s0
	v_mov_b32_e32 v17, s46
	s_sleep 2
	ds_read_b32 v16, v16
	ds_read_b32 v17, v17
	s_waitcnt lgkmcnt(0)
	v_min_i32_e32 v16, v16, v17
	v_cmp_gt_i32_e32 vcc, s1, v16
	s_cbranch_vccnz .LBB0_1423
